# MLA attention: max-subtraction folded into the QK MFMA C operand, exps in place, second half of the row-sum adds kept in the PV phase (31 instead of 42 VALU in the QK phase), on top of v10
# speedup vs baseline: 1.0011x; 1.0011x over previous
.LBB0_436:
	v_add3_u32 v198, s20, v180, v182
	ds_read_b128 v[82:85], v198
	ds_read_b128 v[186:189], v198 offset:32
	s_mulk_i32 s24, 0x4800
	v_add_u32_e32 v223, s24, v185
	v_max_f32_e32 v204, v2, v3
	s_waitcnt lgkmcnt(1)
	v_mfma_f32_32x32x16_bf16 v[82:97], v[82:85], v[98:101], v[206:221]
	v_max3_f32 v204, v204, v4, v5
	v_max3_f32 v204, v204, v6, v7
	v_max3_f32 v204, v204, v8, v9
	v_max3_f32 v204, v204, v10, v11
	v_max3_f32 v204, v204, v12, v13
	v_max3_f32 v204, v204, v14, v15
	v_max3_f32 v204, v204, v16, v17
	s_waitcnt lgkmcnt(0)
	v_mfma_f32_32x32x16_bf16 v[82:97], v[186:189], v[102:105], v[82:97]
	ds_read_b128 v[186:189], v198 offset:64
	ds_read_b128 v[190:193], v198 offset:96
	v_exp_f32_e32 v2, v2
	v_exp_f32_e32 v3, v3
	v_exp_f32_e32 v4, v4
	v_exp_f32_e32 v5, v5
	v_exp_f32_e32 v6, v6
	v_exp_f32_e32 v7, v7
	s_waitcnt lgkmcnt(1)
	v_mfma_f32_32x32x16_bf16 v[82:97], v[186:189], v[106:109], v[82:97]
	v_exp_f32_e32 v8, v8
	v_exp_f32_e32 v9, v9
	v_add_f32_e32 v236, v3, v2
	v_add_f32_e32 v236, v4, v236
	v_add_f32_e32 v236, v5, v236
	v_add_f32_e32 v236, v6, v236
	v_add_f32_e32 v236, v7, v236
	s_waitcnt lgkmcnt(0)
	v_mfma_f32_32x32x16_bf16 v[82:97], v[190:193], v[110:113], v[82:97]
	ds_read_b128 v[186:189], v198 offset:128
	ds_read_b128 v[190:193], v198 offset:160
	v_exp_f32_e32 v10, v10
	v_exp_f32_e32 v11, v11
	v_exp_f32_e32 v12, v12
	v_exp_f32_e32 v13, v13
	v_add_f32_e32 v236, v8, v236
	v_add_f32_e32 v236, v9, v236
	s_waitcnt lgkmcnt(1)
	v_mfma_f32_32x32x16_bf16 v[82:97], v[186:189], v[114:117], v[82:97]
	ds_read_b128 v[186:189], v198 offset:192
	v_exp_f32_e32 v14, v14
	v_exp_f32_e32 v15, v15
	v_exp_f32_e32 v16, v16
	s_waitcnt lgkmcnt(1)
	v_mfma_f32_32x32x16_bf16 v[82:97], v[190:193], v[118:121], v[82:97]
	ds_read_b128 v[190:193], v198 offset:224
	s_waitcnt lgkmcnt(1)
	v_mfma_f32_32x32x16_bf16 v[82:97], v[186:189], v[122:125], v[82:97]
	ds_read_b128 v[186:189], v198 offset:256
	ds_bpermute_b32 v205, v178, v204
	v_exp_f32_e32 v17, v17
	s_waitcnt lgkmcnt(2)
	v_mfma_f32_32x32x16_bf16 v[82:97], v[190:193], v[126:129], v[82:97]
	ds_read_b128 v[190:193], v198 offset:288
	ds_read_b128 v[194:197], v198 offset:320
	ds_read_b128 v[198:201], v198 offset:352
	s_waitcnt lgkmcnt(4)
	v_mfma_f32_32x32x16_bf16 v[82:97], v[186:189], v[130:133], v[82:97]
	ds_read_b128 v[186:189], v223 offset:51264
	s_waitcnt lgkmcnt(3)
	v_mfma_f32_32x32x16_bf16 v[82:97], v[190:193], v[134:137], v[82:97]
	ds_read_b128 v[190:193], v223 offset:51296
	s_waitcnt lgkmcnt(3)
	v_mfma_f32_32x32x16_bf16 v[82:97], v[194:197], v[138:141], v[82:97]
	v_cvt_pk_bf16_f32 v194, v2, v3
	v_cvt_pk_bf16_f32 v195, v4, v5
	v_cvt_pk_bf16_f32 v196, v6, v7
	v_cvt_pk_bf16_f32 v197, v8, v9
	s_waitcnt lgkmcnt(1)
	s_nop 0
	v_mfma_f32_32x32x16_bf16 v[18:33], v[186:189], v[194:197], v[18:33]
	v_cvt_pk_bf16_f32 v186, v10, v11
	v_cvt_pk_bf16_f32 v187, v12, v13
	v_cvt_pk_bf16_f32 v188, v14, v15
	v_cvt_pk_bf16_f32 v189, v16, v17
	s_waitcnt lgkmcnt(0)
	v_max_f32_e32 v222, v204, v205
	v_mfma_f32_32x32x16_bf16 v[18:33], v[190:193], v[186:189], v[18:33]
	ds_read_b128 v[190:193], v223 offset:55872
	ds_read_b128 v[202:205], v223 offset:55904
	ds_read_b128 v[2:5], v223 offset:60512
	ds_read_b128 v[6:9], v223 offset:65088
	s_waitcnt lgkmcnt(3)
	v_mfma_f32_32x32x16_bf16 v[34:49], v[190:193], v[194:197], v[34:49]
	ds_read_b128 v[190:193], v223 offset:60480
	s_waitcnt lgkmcnt(0)
	v_mfma_f32_32x32x16_bf16 v[50:65], v[190:193], v[194:197], v[50:65]
	v_mfma_f32_32x32x16_bf16 v[50:65], v[2:5], v[186:189], v[50:65]
	v_add_f32_e32 v236, v10, v236
	v_add_f32_e32 v236, v11, v236
	v_add_f32_e32 v236, v12, v236
	v_add_f32_e32 v236, v13, v236
	ds_read_b128 v[2:5], v223 offset:65120
	v_mfma_f32_32x32x16_bf16 v[66:81], v[6:9], v[194:197], v[66:81]
	v_add_f32_e32 v236, v14, v236
	v_add_f32_e32 v236, v15, v236
	v_add_f32_e32 v236, v16, v236
	v_add_f32_e32 v236, v17, v236
	s_waitcnt lgkmcnt(0)
	v_mfma_f32_32x32x16_bf16 v[66:81], v[2:5], v[186:189], v[66:81]
	v_add_f32_e32 v183, v183, v236
	v_mfma_f32_32x32x16_bf16 v[34:49], v[202:205], v[186:189], v[34:49]
	v_cmp_lt_f32_e32 vcc, s2, v222
	v_mfma_f32_32x32x16_bf16 v[2:17], v[198:201], v[142:145], v[82:97]
	s_cbranch_vccz .LBB0_438
	v_max_f32_e32 v202, v222, v222
	v_max_f32_e32 v203, 0, v202
	v_exp_f32_e64 v202, -v203
	v_add_f32_e32 v184, v184, v203
	v_mul_f32_e32 v183, v183, v202
	v_pk_mul_f32 v[32:33], v[202:203], v[32:33] op_sel_hi:[0,1]
	v_pk_mul_f32 v[30:31], v[202:203], v[30:31] op_sel_hi:[0,1]
	v_pk_mul_f32 v[28:29], v[202:203], v[28:29] op_sel_hi:[0,1]
	v_pk_mul_f32 v[26:27], v[202:203], v[26:27] op_sel_hi:[0,1]
	v_pk_mul_f32 v[24:25], v[202:203], v[24:25] op_sel_hi:[0,1]
	v_pk_mul_f32 v[22:23], v[202:203], v[22:23] op_sel_hi:[0,1]
	v_pk_mul_f32 v[20:21], v[202:203], v[20:21] op_sel_hi:[0,1]
	v_pk_mul_f32 v[18:19], v[202:203], v[18:19] op_sel_hi:[0,1]
	v_pk_mul_f32 v[48:49], v[202:203], v[48:49] op_sel_hi:[0,1]
	v_pk_mul_f32 v[46:47], v[202:203], v[46:47] op_sel_hi:[0,1]
	v_pk_mul_f32 v[44:45], v[202:203], v[44:45] op_sel_hi:[0,1]
	v_pk_mul_f32 v[42:43], v[202:203], v[42:43] op_sel_hi:[0,1]
	v_pk_mul_f32 v[40:41], v[202:203], v[40:41] op_sel_hi:[0,1]
	v_pk_mul_f32 v[38:39], v[202:203], v[38:39] op_sel_hi:[0,1]
	v_pk_mul_f32 v[36:37], v[202:203], v[36:37] op_sel_hi:[0,1]
	v_pk_mul_f32 v[34:35], v[202:203], v[34:35] op_sel_hi:[0,1]
	v_pk_mul_f32 v[64:65], v[202:203], v[64:65] op_sel_hi:[0,1]
	v_pk_mul_f32 v[62:63], v[202:203], v[62:63] op_sel_hi:[0,1]
	v_pk_mul_f32 v[60:61], v[202:203], v[60:61] op_sel_hi:[0,1]
	v_pk_mul_f32 v[58:59], v[202:203], v[58:59] op_sel_hi:[0,1]
	v_pk_mul_f32 v[56:57], v[202:203], v[56:57] op_sel_hi:[0,1]
	v_pk_mul_f32 v[54:55], v[202:203], v[54:55] op_sel_hi:[0,1]
	v_pk_mul_f32 v[52:53], v[202:203], v[52:53] op_sel_hi:[0,1]
	v_pk_mul_f32 v[50:51], v[202:203], v[50:51] op_sel_hi:[0,1]
	v_pk_mul_f32 v[80:81], v[202:203], v[80:81] op_sel_hi:[0,1]
	v_pk_mul_f32 v[78:79], v[202:203], v[78:79] op_sel_hi:[0,1]
	v_pk_mul_f32 v[76:77], v[202:203], v[76:77] op_sel_hi:[0,1]
	v_pk_mul_f32 v[74:75], v[202:203], v[74:75] op_sel_hi:[0,1]
	v_pk_mul_f32 v[72:73], v[202:203], v[72:73] op_sel_hi:[0,1]
	v_pk_mul_f32 v[70:71], v[202:203], v[70:71] op_sel_hi:[0,1]
	v_pk_mul_f32 v[68:69], v[202:203], v[68:69] op_sel_hi:[0,1]
	v_pk_mul_f32 v[66:67], v[202:203], v[66:67] op_sel_hi:[0,1]
	v_sub_f32_e32 v2, v2, v203
	v_sub_f32_e32 v3, v3, v203
	v_sub_f32_e32 v4, v4, v203
	v_sub_f32_e32 v5, v5, v203
	v_sub_f32_e32 v6, v6, v203
	v_sub_f32_e32 v7, v7, v203
	v_sub_f32_e32 v8, v8, v203
	v_sub_f32_e32 v9, v9, v203
	v_sub_f32_e32 v10, v10, v203
	v_sub_f32_e32 v11, v11, v203
	v_sub_f32_e32 v12, v12, v203
	v_sub_f32_e32 v13, v13, v203
	v_sub_f32_e32 v14, v14, v203
	v_sub_f32_e32 v15, v15, v203
	v_sub_f32_e32 v16, v16, v203
	v_sub_f32_e32 v17, v17, v203
	v_sub_f32_e32 v206, v206, v203
	v_sub_f32_e32 v207, v207, v203
	v_sub_f32_e32 v208, v208, v203
	v_sub_f32_e32 v209, v209, v203
	v_sub_f32_e32 v210, v210, v203
	v_sub_f32_e32 v211, v211, v203
	v_sub_f32_e32 v212, v212, v203
	v_sub_f32_e32 v213, v213, v203
	v_sub_f32_e32 v214, v214, v203
	v_sub_f32_e32 v215, v215, v203
	v_sub_f32_e32 v216, v216, v203
	v_sub_f32_e32 v217, v217, v203
	v_sub_f32_e32 v218, v218, v203
	v_sub_f32_e32 v219, v219, v203
	v_sub_f32_e32 v220, v220, v203
	v_sub_f32_e32 v221, v221, v203

.LBB0_443:
	v_add3_u32 v198, s20, v180, v182
	ds_read_b128 v[82:85], v198 offset:12800
	ds_read_b128 v[186:189], v198 offset:12832
	s_mul_i32 s12, s19, 0x4800
	v_add_u32_e32 v223, s12, v185
	v_max_f32_e32 v204, v2, v3
	s_waitcnt lgkmcnt(1)
	v_mfma_f32_32x32x16_bf16 v[82:97], v[82:85], v[98:101], v[206:221]
	v_max3_f32 v204, v204, v4, v5
	v_max3_f32 v204, v204, v6, v7
	v_max3_f32 v204, v204, v8, v9
	v_max3_f32 v204, v204, v10, v11
	v_max3_f32 v204, v204, v12, v13
	v_max3_f32 v204, v204, v14, v15
	v_max3_f32 v204, v204, v16, v17
	s_waitcnt lgkmcnt(0)
	v_mfma_f32_32x32x16_bf16 v[82:97], v[186:189], v[102:105], v[82:97]
	ds_read_b128 v[186:189], v198 offset:12864
	ds_read_b128 v[190:193], v198 offset:12896
	v_exp_f32_e32 v2, v2
	v_exp_f32_e32 v3, v3
	v_exp_f32_e32 v4, v4
	v_exp_f32_e32 v5, v5
	v_exp_f32_e32 v6, v6
	v_exp_f32_e32 v7, v7
	s_waitcnt lgkmcnt(1)
	v_mfma_f32_32x32x16_bf16 v[82:97], v[186:189], v[106:109], v[82:97]
	v_exp_f32_e32 v8, v8
	v_exp_f32_e32 v9, v9
	v_add_f32_e32 v236, v3, v2
	v_add_f32_e32 v236, v4, v236
	v_add_f32_e32 v236, v5, v236
	v_add_f32_e32 v236, v6, v236
	v_add_f32_e32 v236, v7, v236
	s_waitcnt lgkmcnt(0)
	v_mfma_f32_32x32x16_bf16 v[82:97], v[190:193], v[110:113], v[82:97]
	ds_read_b128 v[186:189], v198 offset:12928
	ds_read_b128 v[190:193], v198 offset:12960
	v_exp_f32_e32 v10, v10
	v_exp_f32_e32 v11, v11
	v_exp_f32_e32 v12, v12
	v_exp_f32_e32 v13, v13
	v_add_f32_e32 v236, v8, v236
	v_add_f32_e32 v236, v9, v236
	s_waitcnt lgkmcnt(1)
	v_mfma_f32_32x32x16_bf16 v[82:97], v[186:189], v[114:117], v[82:97]
	ds_read_b128 v[186:189], v198 offset:12992
	v_exp_f32_e32 v14, v14
	v_exp_f32_e32 v15, v15
	v_exp_f32_e32 v16, v16
	s_waitcnt lgkmcnt(1)
	v_mfma_f32_32x32x16_bf16 v[82:97], v[190:193], v[118:121], v[82:97]
	ds_read_b128 v[190:193], v198 offset:13024
	s_waitcnt lgkmcnt(1)
	v_mfma_f32_32x32x16_bf16 v[82:97], v[186:189], v[122:125], v[82:97]
	ds_read_b128 v[186:189], v198 offset:13056
	ds_bpermute_b32 v205, v178, v204
	v_exp_f32_e32 v17, v17
	s_waitcnt lgkmcnt(2)
	v_mfma_f32_32x32x16_bf16 v[82:97], v[190:193], v[126:129], v[82:97]
	ds_read_b128 v[190:193], v198 offset:13088
	ds_read_b128 v[194:197], v198 offset:13120
	ds_read_b128 v[198:201], v198 offset:13152
	s_waitcnt lgkmcnt(4)
	v_mfma_f32_32x32x16_bf16 v[82:97], v[186:189], v[130:133], v[82:97]
	ds_read_b128 v[186:189], v223 offset:51200
	s_waitcnt lgkmcnt(3)
	v_mfma_f32_32x32x16_bf16 v[82:97], v[190:193], v[134:137], v[82:97]
	ds_read_b128 v[190:193], v223 offset:51232
	s_waitcnt lgkmcnt(3)
	v_mfma_f32_32x32x16_bf16 v[82:97], v[194:197], v[138:141], v[82:97]
	v_cvt_pk_bf16_f32 v194, v2, v3
	v_cvt_pk_bf16_f32 v195, v4, v5
	v_cvt_pk_bf16_f32 v196, v6, v7
	v_cvt_pk_bf16_f32 v197, v8, v9
	s_waitcnt lgkmcnt(1)
	s_nop 0
	v_mfma_f32_32x32x16_bf16 v[18:33], v[186:189], v[194:197], v[18:33]
	v_cvt_pk_bf16_f32 v186, v10, v11
	v_cvt_pk_bf16_f32 v187, v12, v13
	v_cvt_pk_bf16_f32 v188, v14, v15
	v_cvt_pk_bf16_f32 v189, v16, v17
	s_waitcnt lgkmcnt(0)
	v_max_f32_e32 v222, v204, v205
	v_mfma_f32_32x32x16_bf16 v[18:33], v[190:193], v[186:189], v[18:33]
	ds_read_b128 v[190:193], v223 offset:55808
	ds_read_b128 v[202:205], v223 offset:55840
	ds_read_b128 v[2:5], v223 offset:60448
	ds_read_b128 v[6:9], v223 offset:65024
	s_waitcnt lgkmcnt(3)
	v_mfma_f32_32x32x16_bf16 v[34:49], v[190:193], v[194:197], v[34:49]
	ds_read_b128 v[190:193], v223 offset:60416
	s_waitcnt lgkmcnt(0)
	v_mfma_f32_32x32x16_bf16 v[50:65], v[190:193], v[194:197], v[50:65]
	v_mfma_f32_32x32x16_bf16 v[50:65], v[2:5], v[186:189], v[50:65]
	v_add_f32_e32 v236, v10, v236
	v_add_f32_e32 v236, v11, v236
	v_add_f32_e32 v236, v12, v236
	v_add_f32_e32 v236, v13, v236
	ds_read_b128 v[2:5], v223 offset:65056
	v_mfma_f32_32x32x16_bf16 v[66:81], v[6:9], v[194:197], v[66:81]
	v_add_f32_e32 v236, v14, v236
	v_add_f32_e32 v236, v15, v236
	v_add_f32_e32 v236, v16, v236
	v_add_f32_e32 v236, v17, v236
	s_waitcnt lgkmcnt(0)
	v_mfma_f32_32x32x16_bf16 v[66:81], v[2:5], v[186:189], v[66:81]
	v_add_f32_e32 v183, v183, v236
	v_mfma_f32_32x32x16_bf16 v[34:49], v[202:205], v[186:189], v[34:49]
	v_cmp_lt_f32_e32 vcc, s2, v222
	v_mfma_f32_32x32x16_bf16 v[2:17], v[198:201], v[142:145], v[82:97]
	s_cbranch_vccz .LBB0_445
	v_max_f32_e32 v202, v222, v222
	v_max_f32_e32 v203, 0, v202
	v_exp_f32_e64 v202, -v203
	v_add_f32_e32 v184, v184, v203
	v_mul_f32_e32 v183, v183, v202
	v_pk_mul_f32 v[32:33], v[32:33], v[202:203] op_sel_hi:[1,0]
	v_pk_mul_f32 v[30:31], v[30:31], v[202:203] op_sel_hi:[1,0]
	v_pk_mul_f32 v[28:29], v[28:29], v[202:203] op_sel_hi:[1,0]
	v_pk_mul_f32 v[26:27], v[26:27], v[202:203] op_sel_hi:[1,0]
	v_pk_mul_f32 v[24:25], v[24:25], v[202:203] op_sel_hi:[1,0]
	v_pk_mul_f32 v[22:23], v[22:23], v[202:203] op_sel_hi:[1,0]
	v_pk_mul_f32 v[20:21], v[20:21], v[202:203] op_sel_hi:[1,0]
	v_pk_mul_f32 v[18:19], v[18:19], v[202:203] op_sel_hi:[1,0]
	v_pk_mul_f32 v[48:49], v[202:203], v[48:49] op_sel_hi:[0,1]
	v_pk_mul_f32 v[46:47], v[202:203], v[46:47] op_sel_hi:[0,1]
	v_pk_mul_f32 v[44:45], v[202:203], v[44:45] op_sel_hi:[0,1]
	v_pk_mul_f32 v[42:43], v[202:203], v[42:43] op_sel_hi:[0,1]
	v_pk_mul_f32 v[40:41], v[202:203], v[40:41] op_sel_hi:[0,1]
	v_pk_mul_f32 v[38:39], v[202:203], v[38:39] op_sel_hi:[0,1]
	v_pk_mul_f32 v[36:37], v[202:203], v[36:37] op_sel_hi:[0,1]
	v_pk_mul_f32 v[34:35], v[202:203], v[34:35] op_sel_hi:[0,1]
	v_pk_mul_f32 v[64:65], v[202:203], v[64:65] op_sel_hi:[0,1]
	v_pk_mul_f32 v[62:63], v[202:203], v[62:63] op_sel_hi:[0,1]
	v_pk_mul_f32 v[60:61], v[202:203], v[60:61] op_sel_hi:[0,1]
	v_pk_mul_f32 v[58:59], v[202:203], v[58:59] op_sel_hi:[0,1]
	v_pk_mul_f32 v[56:57], v[202:203], v[56:57] op_sel_hi:[0,1]
	v_pk_mul_f32 v[54:55], v[202:203], v[54:55] op_sel_hi:[0,1]
	v_pk_mul_f32 v[52:53], v[202:203], v[52:53] op_sel_hi:[0,1]
	v_pk_mul_f32 v[50:51], v[202:203], v[50:51] op_sel_hi:[0,1]
	v_pk_mul_f32 v[80:81], v[202:203], v[80:81] op_sel_hi:[0,1]
	v_pk_mul_f32 v[78:79], v[202:203], v[78:79] op_sel_hi:[0,1]
	v_pk_mul_f32 v[76:77], v[202:203], v[76:77] op_sel_hi:[0,1]
	v_pk_mul_f32 v[74:75], v[202:203], v[74:75] op_sel_hi:[0,1]
	v_pk_mul_f32 v[72:73], v[202:203], v[72:73] op_sel_hi:[0,1]
	v_pk_mul_f32 v[70:71], v[202:203], v[70:71] op_sel_hi:[0,1]
	v_pk_mul_f32 v[68:69], v[202:203], v[68:69] op_sel_hi:[0,1]
	v_pk_mul_f32 v[66:67], v[202:203], v[66:67] op_sel_hi:[0,1]
	v_sub_f32_e32 v2, v2, v203
	v_sub_f32_e32 v3, v3, v203
	v_sub_f32_e32 v4, v4, v203
	v_sub_f32_e32 v5, v5, v203
	v_sub_f32_e32 v6, v6, v203
	v_sub_f32_e32 v7, v7, v203
	v_sub_f32_e32 v8, v8, v203
	v_sub_f32_e32 v9, v9, v203
	v_sub_f32_e32 v10, v10, v203
	v_sub_f32_e32 v11, v11, v203
	v_sub_f32_e32 v12, v12, v203
	v_sub_f32_e32 v13, v13, v203
	v_sub_f32_e32 v14, v14, v203
	v_sub_f32_e32 v15, v15, v203
	v_sub_f32_e32 v16, v16, v203
	v_sub_f32_e32 v17, v17, v203
	v_sub_f32_e32 v206, v206, v203
	v_sub_f32_e32 v207, v207, v203
	v_sub_f32_e32 v208, v208, v203
	v_sub_f32_e32 v209, v209, v203
	v_sub_f32_e32 v210, v210, v203
	v_sub_f32_e32 v211, v211, v203
	v_sub_f32_e32 v212, v212, v203
	v_sub_f32_e32 v213, v213, v203
	v_sub_f32_e32 v214, v214, v203
	v_sub_f32_e32 v215, v215, v203
	v_sub_f32_e32 v216, v216, v203
	v_sub_f32_e32 v217, v217, v203
	v_sub_f32_e32 v218, v218, v203
	v_sub_f32_e32 v219, v219, v203
	v_sub_f32_e32 v220, v220, v203
	v_sub_f32_e32 v221, v221, v203
